# scan loop emitted with every 8-byte instruction on an 8-byte boundary (184-byte steps, p2align 3 at the loop head) so later edits cannot shift it out of phase
# baseline (speedup 1.0000x reference)
; #define LAS __attribute__((address_space(3)))
; __device__ __forceinline__ float sum16(float x) { x = dpp_add<0xB1>(x); x = dpp_add<0x4E>(x); x = dpp_add<0x141>(x); x = dpp_add<0x140>(x); return x; }
; __device__ __forceinline__ void scan_step(f32x4& S, const ScanOps& o, LAS float* yp) {
;     f32x2 S0 = {S[0], S[1]}, S1 = {S[2], S[3]};
;     const f32x2 k0 = {o.kk[0], o.kk[1]}, k1 = {o.kk[2], o.kk[3]};
;     f32x2 t = S0 * k0; t = S1 * k1 + t;
;     const float sa = -sum16(t[0] + t[1]);
;     const f32x2 sav = {sa, sa}, vv = {o.v, o.v};
;     const f32x2 a0 = {o.ka[0], o.ka[1]}, a1 = {o.ka[2], o.ka[3]}, p0 = {o.kp[0], o.kp[1]}, p1 = {o.kp[2], o.kp[3]}, w0 = {o.w[0], o.w[1]}, w1 = {o.w[2], o.w[3]};
;     f32x2 u0 = a0 * sav; u0 = p0 * vv + u0; S0 = S0 * w0 + u0;
;     f32x2 u1 = a1 * sav; u1 = p1 * vv + u1; S1 = S1 * w1 + u1;
;     const f32x2 r0 = {o.rr[0], o.rr[1]}, r1 = {o.rr[2], o.rr[3]};
;     f32x2 y = S0 * r0; y = S1 * r1 + y;
;     *yp = y[0] + y[1];
;     S = (f32x4){S0[0], S0[1], S1[0], S1[1]};
; __device__ __forceinline__ void scan_unit(const Ctx& p, int chain, int rq, LAS unsigned char* lds) {
;     ...
;         for (int ci = 0; ci < nch; ++ci) {
;             __syncthreads();
;             const LAS float* OP = B0 + (ci & 1) * SBUF_F + 4 * cl;
;             const LAS float* VP = B0 + (ci & 1) * SBUF_F + SCH * 320 + il * 16;
;             LAS float* Y = YB + (ci & 1) * YP_F + il * 16 + cl;
;             ScanOps oa, ob;
;             scan_load(oa, OP, VP, 0);
;             f32x2 vv = *(const LAS f32x2*)VP;
; #pragma unroll 1
;             for (int t = 0; t < SCH; t += 2) {
;                 scan_load(ob, OP, VP, t + 1);
;                 oa.v = vv[0]; ob.v = vv[1];
;                 scan_step(S, oa, Y + t * 256);
;                 scan_load(oa, OP, VP, (t + 2) & (SCH - 1));
;                 vv = *(const LAS f32x2*)(VP + ((t + 2) & (SCH - 1)));
;                 scan_step(S, ob, Y + (t + 1) * 256);
;             }
;         }
.LBB0_1711:
	s_and_b64 vcc, exec, s[2:3]
	s_cbranch_vccz .LBB0_1750
	s_add_i32 s2, 0, 0x23528
	s_waitcnt vmcnt(0)
	v_mov_b32_e32 v0, s2
	ds_read_b64 v[0:1], v0
	v_readfirstlane_b32 s8, v180
	s_mov_b32 s10, 0
	s_cmpk_lt_u32 s8, 0x100
	s_mov_b64 s[2:3], -1
	s_waitcnt lgkmcnt(0)
	v_readfirstlane_b32 s4, v0
	v_readfirstlane_b32 s5, v1
	s_barrier
	s_cbranch_scc0 .LBB0_1718
	s_add_i32 s2, 0, 0x23520
	v_mov_b32_e32 v0, s2
	ds_read_b64 v[0:1], v0
	v_bfe_u32 v2, v180, 4, 2
	v_and_b32_e32 v3, 15, v180
	s_lshr_b32 s2, s8, 4
	s_lshl_b32 s8, s8, 2
	v_and_or_b32 v27, s2, 12, v2
	s_waitcnt lgkmcnt(0)
	v_readfirstlane_b32 s2, v0
	v_lshlrev_b32_e32 v26, 2, v3
	s_and_b32 s8, s8, 0x300
	v_lshlrev_b32_e32 v0, 6, v2
	v_or3_b32 v0, s8, v0, v26
	v_add_u32_e32 v0, 0, v0
	v_add_u32_e32 v29, 0xa800, v0
	v_lshl_add_u32 v0, v3, 4, 0
	v_add_u32_e32 v30, 0x500, v0
	v_mov_b32_e32 v0, 0
	v_readfirstlane_b32 s3, v1
	v_lshlrev_b32_e32 v28, 4, v27
	s_mov_b64 s[8:9], 0
	s_movk_i32 s11, 0x5400
	v_mov_b32_e32 v1, v0
	v_mov_b32_e32 v2, v0
	v_mov_b32_e32 v3, v0
	s_setprio 2
	.p2align 3
.LBB0_1714:
	s_and_b32 s12, s10, 1
	s_mulk_i32 s12, 0x5400
	s_lshl_b32 s13, s10, 14
	s_nop 0
	v_lshl_add_u32 v31, v26, 2, s12
	s_and_b32 s13, s13, 0x4000
	v_lshl_add_u32 v32, v28, 2, s12
	v_add_u32_e32 v33, s13, v29
	s_waitcnt lgkmcnt(0)
	s_barrier
	s_nop 0
	ds_read_b128 v[60:63], v31 offset:256
	ds_read_b128 v[64:67], v31 offset:768
	ds_read_b128 v[40:43], v32 offset:20480
	ds_read_b128 v[68:71], v31 offset:0
	ds_read_b128 v[72:75], v31 offset:512
	ds_read_b128 v[76:79], v31 offset:1024
	ds_read_b128 v[44:47], v32 offset:20496
	ds_read_b128 v[48:51], v32 offset:20512
	ds_read_b128 v[52:55], v32 offset:20528
	ds_read_b128 v[80:83], v31 offset:1536
	ds_read_b128 v[84:87], v31 offset:2048
	ds_read_b128 v[88:91], v31 offset:1280
	ds_read_b128 v[92:95], v31 offset:1792
	ds_read_b128 v[96:99], v31 offset:2304
	s_waitcnt lgkmcnt(13)
	v_mul_f32_e32 v100, v0, v60
	v_fmac_f32_e32 v100, v1, v61
	v_fmac_f32_e32 v100, v2, v62
	v_fmac_f32_e32 v100, v3, v63
	s_waitcnt lgkmcnt(11)
	v_mul_f32_e32 v104, v64, v40
	v_mul_f32_e32 v105, v65, v40
	v_add_f32_dpp v100, v100, v100 quad_perm:[1,0,3,2] row_mask:0xf bank_mask:0xf bound_ctrl:1
	v_mul_f32_e32 v106, v66, v40
	v_mul_f32_e32 v107, v67, v40
	v_add_f32_dpp v100, v100, v100 quad_perm:[2,3,0,1] row_mask:0xf bank_mask:0xf bound_ctrl:1
	s_waitcnt lgkmcnt(10)
	v_fmac_f32_e32 v104, v0, v68
	v_fmac_f32_e64 v105, v1, v69
	v_add_f32_dpp v100, v100, v100 row_half_mirror row_mask:0xf bank_mask:0xf bound_ctrl:1
	v_fmac_f32_e32 v106, v2, v70
	v_fmac_f32_e32 v107, v3, v71
	v_add_f32_dpp v100, v100, v100 row_mirror row_mask:0xf bank_mask:0xf bound_ctrl:1
	s_waitcnt lgkmcnt(9)
	s_nop 0
	v_fma_f32 v0, -v72, v100, v104
	v_fma_f32 v1, -v73, v100, v105
	v_fma_f32 v2, -v74, v100, v106
	v_fma_f32 v3, -v75, v100, v107
	s_waitcnt lgkmcnt(8)
	v_mul_f32_e32 v101, v0, v76
	v_fmac_f32_e32 v101, v1, v77
	v_fmac_f32_e32 v101, v2, v78
	v_fmac_f32_e64 v101, v3, v79
	ds_write_b32 v33, v101 offset:0
	ds_read_b128 v[60:63], v31 offset:2816
	ds_read_b128 v[64:67], v31 offset:3328
	ds_read_b128 v[68:71], v31 offset:2560
	ds_read_b128 v[72:75], v31 offset:3072
	ds_read_b128 v[76:79], v31 offset:3584
	s_waitcnt lgkmcnt(6)
	v_mul_f32_e32 v100, v0, v80
	v_fmac_f32_e32 v100, v1, v81
	v_fmac_f32_e32 v100, v2, v82
	v_fmac_f32_e32 v100, v3, v83
	v_mul_f32_e32 v104, v84, v41
	v_mul_f32_e64 v105, v85, v41
	v_add_f32_dpp v100, v100, v100 quad_perm:[1,0,3,2] row_mask:0xf bank_mask:0xf bound_ctrl:1
	v_mul_f32_e32 v106, v86, v41
	v_mul_f32_e32 v107, v87, v41
	v_add_f32_dpp v100, v100, v100 quad_perm:[2,3,0,1] row_mask:0xf bank_mask:0xf bound_ctrl:1
	v_fmac_f32_e32 v104, v0, v88
	v_fmac_f32_e32 v105, v1, v89
	v_add_f32_dpp v100, v100, v100 row_half_mirror row_mask:0xf bank_mask:0xf bound_ctrl:1
	v_fmac_f32_e32 v106, v2, v90
	v_fmac_f32_e32 v107, v3, v91
	v_add_f32_dpp v100, v100, v100 row_mirror row_mask:0xf bank_mask:0xf bound_ctrl:1
	v_fma_f32 v0, -v92, v100, v104
	v_fma_f32 v1, -v93, v100, v105
	v_fma_f32 v2, -v94, v100, v106
	v_fma_f32 v3, -v95, v100, v107
	v_mul_f32_e32 v101, v0, v96
	v_fmac_f32_e32 v101, v1, v97
	v_fmac_f32_e32 v101, v2, v98
	v_fmac_f32_e32 v101, v3, v99
	ds_write_b32 v33, v101 offset:1024
	ds_read_b128 v[80:83], v31 offset:4096
	ds_read_b128 v[84:87], v31 offset:4608
	ds_read_b128 v[88:91], v31 offset:3840
	ds_read_b128 v[92:95], v31 offset:4352
	ds_read_b128 v[96:99], v31 offset:4864
	s_waitcnt lgkmcnt(6)
	v_mul_f32_e32 v100, v0, v60
	v_fmac_f32_e32 v100, v1, v61
	v_fmac_f32_e32 v100, v2, v62
	v_fmac_f32_e32 v100, v3, v63
	v_mul_f32_e32 v104, v64, v42
	v_mul_f32_e64 v105, v65, v42
	v_add_f32_dpp v100, v100, v100 quad_perm:[1,0,3,2] row_mask:0xf bank_mask:0xf bound_ctrl:1
	v_mul_f32_e32 v106, v66, v42
	v_mul_f32_e32 v107, v67, v42
	v_add_f32_dpp v100, v100, v100 quad_perm:[2,3,0,1] row_mask:0xf bank_mask:0xf bound_ctrl:1
	v_fmac_f32_e32 v104, v0, v68
	v_fmac_f32_e32 v105, v1, v69
	v_add_f32_dpp v100, v100, v100 row_half_mirror row_mask:0xf bank_mask:0xf bound_ctrl:1
	v_fmac_f32_e32 v106, v2, v70
	v_fmac_f32_e32 v107, v3, v71
	v_add_f32_dpp v100, v100, v100 row_mirror row_mask:0xf bank_mask:0xf bound_ctrl:1
	v_fma_f32 v0, -v72, v100, v104
	v_fma_f32 v1, -v73, v100, v105
	v_fma_f32 v2, -v74, v100, v106
	v_fma_f32 v3, -v75, v100, v107
	v_mul_f32_e32 v101, v0, v76
	v_fmac_f32_e32 v101, v1, v77
	v_fmac_f32_e32 v101, v2, v78
	v_fmac_f32_e32 v101, v3, v79
	ds_write_b32 v33, v101 offset:2048
	ds_read_b128 v[60:63], v31 offset:5376
	ds_read_b128 v[64:67], v31 offset:5888
	ds_read_b128 v[68:71], v31 offset:5120
	ds_read_b128 v[72:75], v31 offset:5632
	ds_read_b128 v[76:79], v31 offset:6144
	s_waitcnt lgkmcnt(6)
; #define LAS __attribute__((address_space(3)))
; __device__ __forceinline__ float sum16(float x) { x = dpp_add<0xB1>(x); x = dpp_add<0x4E>(x); x = dpp_add<0x141>(x); x = dpp_add<0x140>(x); return x; }
; __device__ __forceinline__ void scan_step(f32x4& S, const ScanOps& o, LAS float* yp) {
;     f32x2 S0 = {S[0], S[1]}, S1 = {S[2], S[3]};
;     const f32x2 k0 = {o.kk[0], o.kk[1]}, k1 = {o.kk[2], o.kk[3]};
;     f32x2 t = S0 * k0; t = S1 * k1 + t;
;     const float sa = -sum16(t[0] + t[1]);
;     const f32x2 sav = {sa, sa}, vv = {o.v, o.v};
;     const f32x2 a0 = {o.ka[0], o.ka[1]}, a1 = {o.ka[2], o.ka[3]}, p0 = {o.kp[0], o.kp[1]}, p1 = {o.kp[2], o.kp[3]}, w0 = {o.w[0], o.w[1]}, w1 = {o.w[2], o.w[3]};
;     f32x2 u0 = a0 * sav; u0 = p0 * vv + u0; S0 = S0 * w0 + u0;
;     f32x2 u1 = a1 * sav; u1 = p1 * vv + u1; S1 = S1 * w1 + u1;
;     const f32x2 r0 = {o.rr[0], o.rr[1]}, r1 = {o.rr[2], o.rr[3]};
;     f32x2 y = S0 * r0; y = S1 * r1 + y;
;     *yp = y[0] + y[1];
;     S = (f32x4){S0[0], S0[1], S1[0], S1[1]};
; }
; __device__ __forceinline__ void scan_unit(const Ctx& p, int chain, int rq, LAS unsigned char* lds) {
;     ...
;             for (int t = 0; t < SCH; t += 2) {
;                 scan_load(ob, OP, VP, t + 1);
;                 oa.v = vv[0]; ob.v = vv[1];
;                 scan_step(S, oa, Y + t * 256);
;                 scan_load(oa, OP, VP, (t + 2) & (SCH - 1));
;                 vv = *(const LAS f32x2*)(VP + ((t + 2) & (SCH - 1)));
;                 scan_step(S, ob, Y + (t + 1) * 256);
;             }
	v_mul_f32_e32 v100, v0, v80
	v_fmac_f32_e32 v100, v1, v81
	v_fmac_f32_e32 v100, v2, v82
	v_fmac_f32_e32 v100, v3, v83
	v_mul_f32_e32 v104, v84, v43
	v_mul_f32_e64 v105, v85, v43
	v_add_f32_dpp v100, v100, v100 quad_perm:[1,0,3,2] row_mask:0xf bank_mask:0xf bound_ctrl:1
	v_mul_f32_e32 v106, v86, v43
	v_mul_f32_e32 v107, v87, v43
	v_add_f32_dpp v100, v100, v100 quad_perm:[2,3,0,1] row_mask:0xf bank_mask:0xf bound_ctrl:1
	v_fmac_f32_e32 v104, v0, v88
	v_fmac_f32_e32 v105, v1, v89
	v_add_f32_dpp v100, v100, v100 row_half_mirror row_mask:0xf bank_mask:0xf bound_ctrl:1
	v_fmac_f32_e32 v106, v2, v90
	v_fmac_f32_e32 v107, v3, v91
	v_add_f32_dpp v100, v100, v100 row_mirror row_mask:0xf bank_mask:0xf bound_ctrl:1
	v_fma_f32 v0, -v92, v100, v104
	v_fma_f32 v1, -v93, v100, v105
	v_fma_f32 v2, -v94, v100, v106
	v_fma_f32 v3, -v95, v100, v107
	v_mul_f32_e32 v101, v0, v96
	v_fmac_f32_e32 v101, v1, v97
	v_fmac_f32_e32 v101, v2, v98
	v_fmac_f32_e32 v101, v3, v99
	ds_write_b32 v33, v101 offset:3072
	ds_read_b128 v[80:83], v31 offset:6656
	ds_read_b128 v[84:87], v31 offset:7168
	ds_read_b128 v[88:91], v31 offset:6400
	ds_read_b128 v[92:95], v31 offset:6912
	ds_read_b128 v[96:99], v31 offset:7424
	s_waitcnt lgkmcnt(6)
	v_mul_f32_e32 v100, v0, v60
	v_fmac_f32_e32 v100, v1, v61
	v_fmac_f32_e32 v100, v2, v62
	v_fmac_f32_e32 v100, v3, v63
	v_mul_f32_e32 v104, v64, v44
	v_mul_f32_e64 v105, v65, v44
	v_add_f32_dpp v100, v100, v100 quad_perm:[1,0,3,2] row_mask:0xf bank_mask:0xf bound_ctrl:1
	v_mul_f32_e32 v106, v66, v44
	v_mul_f32_e32 v107, v67, v44
	v_add_f32_dpp v100, v100, v100 quad_perm:[2,3,0,1] row_mask:0xf bank_mask:0xf bound_ctrl:1
	v_fmac_f32_e32 v104, v0, v68
	v_fmac_f32_e32 v105, v1, v69
	v_add_f32_dpp v100, v100, v100 row_half_mirror row_mask:0xf bank_mask:0xf bound_ctrl:1
	v_fmac_f32_e32 v106, v2, v70
	v_fmac_f32_e32 v107, v3, v71
	v_add_f32_dpp v100, v100, v100 row_mirror row_mask:0xf bank_mask:0xf bound_ctrl:1
	v_fma_f32 v0, -v72, v100, v104
	v_fma_f32 v1, -v73, v100, v105
	v_fma_f32 v2, -v74, v100, v106
	v_fma_f32 v3, -v75, v100, v107
	v_mul_f32_e32 v101, v0, v76
	v_fmac_f32_e32 v101, v1, v77
	v_fmac_f32_e32 v101, v2, v78
	v_fmac_f32_e32 v101, v3, v79
	ds_write_b32 v33, v101 offset:4096
	ds_read_b128 v[60:63], v31 offset:7936
	ds_read_b128 v[64:67], v31 offset:8448
	ds_read_b128 v[68:71], v31 offset:7680
	ds_read_b128 v[72:75], v31 offset:8192
	ds_read_b128 v[76:79], v31 offset:8704
	s_waitcnt lgkmcnt(6)
	v_mul_f32_e32 v100, v0, v80
	v_fmac_f32_e32 v100, v1, v81
	v_fmac_f32_e32 v100, v2, v82
	v_fmac_f32_e32 v100, v3, v83
	v_mul_f32_e32 v104, v84, v45
	v_mul_f32_e64 v105, v85, v45
	v_add_f32_dpp v100, v100, v100 quad_perm:[1,0,3,2] row_mask:0xf bank_mask:0xf bound_ctrl:1
	v_mul_f32_e32 v106, v86, v45
	v_mul_f32_e32 v107, v87, v45
	v_add_f32_dpp v100, v100, v100 quad_perm:[2,3,0,1] row_mask:0xf bank_mask:0xf bound_ctrl:1
	v_fmac_f32_e32 v104, v0, v88
	v_fmac_f32_e32 v105, v1, v89
	v_add_f32_dpp v100, v100, v100 row_half_mirror row_mask:0xf bank_mask:0xf bound_ctrl:1
	v_fmac_f32_e32 v106, v2, v90
	v_fmac_f32_e32 v107, v3, v91
	v_add_f32_dpp v100, v100, v100 row_mirror row_mask:0xf bank_mask:0xf bound_ctrl:1
	v_fma_f32 v0, -v92, v100, v104
	v_fma_f32 v1, -v93, v100, v105
	v_fma_f32 v2, -v94, v100, v106
	v_fma_f32 v3, -v95, v100, v107
	v_mul_f32_e32 v101, v0, v96
	v_fmac_f32_e32 v101, v1, v97
	v_fmac_f32_e32 v101, v2, v98
	v_fmac_f32_e32 v101, v3, v99
	ds_write_b32 v33, v101 offset:5120
	ds_read_b128 v[80:83], v31 offset:9216
	ds_read_b128 v[84:87], v31 offset:9728
	ds_read_b128 v[88:91], v31 offset:8960
	ds_read_b128 v[92:95], v31 offset:9472
	ds_read_b128 v[96:99], v31 offset:9984
	s_waitcnt lgkmcnt(6)
	v_mul_f32_e32 v100, v0, v60
	v_fmac_f32_e32 v100, v1, v61
	v_fmac_f32_e32 v100, v2, v62
	v_fmac_f32_e32 v100, v3, v63
	v_mul_f32_e32 v104, v64, v46
	v_mul_f32_e64 v105, v65, v46
	v_add_f32_dpp v100, v100, v100 quad_perm:[1,0,3,2] row_mask:0xf bank_mask:0xf bound_ctrl:1
	v_mul_f32_e32 v106, v66, v46
	v_mul_f32_e32 v107, v67, v46
	v_add_f32_dpp v100, v100, v100 quad_perm:[2,3,0,1] row_mask:0xf bank_mask:0xf bound_ctrl:1
	v_fmac_f32_e32 v104, v0, v68
	v_fmac_f32_e32 v105, v1, v69
	v_add_f32_dpp v100, v100, v100 row_half_mirror row_mask:0xf bank_mask:0xf bound_ctrl:1
	v_fmac_f32_e32 v106, v2, v70
	v_fmac_f32_e32 v107, v3, v71
	v_add_f32_dpp v100, v100, v100 row_mirror row_mask:0xf bank_mask:0xf bound_ctrl:1
	v_fma_f32 v0, -v72, v100, v104
	v_fma_f32 v1, -v73, v100, v105
	v_fma_f32 v2, -v74, v100, v106
	v_fma_f32 v3, -v75, v100, v107
	v_mul_f32_e32 v101, v0, v76
	v_fmac_f32_e32 v101, v1, v77
	v_fmac_f32_e32 v101, v2, v78
	v_fmac_f32_e32 v101, v3, v79
	ds_write_b32 v33, v101 offset:6144
	ds_read_b128 v[60:63], v31 offset:10496
	ds_read_b128 v[64:67], v31 offset:11008
	ds_read_b128 v[68:71], v31 offset:10240
	ds_read_b128 v[72:75], v31 offset:10752
	ds_read_b128 v[76:79], v31 offset:11264
	s_waitcnt lgkmcnt(6)
	v_mul_f32_e32 v100, v0, v80
	v_fmac_f32_e32 v100, v1, v81
	v_fmac_f32_e32 v100, v2, v82
	v_fmac_f32_e32 v100, v3, v83
	v_mul_f32_e32 v104, v84, v47
	v_mul_f32_e64 v105, v85, v47
	v_add_f32_dpp v100, v100, v100 quad_perm:[1,0,3,2] row_mask:0xf bank_mask:0xf bound_ctrl:1
	v_mul_f32_e32 v106, v86, v47
	v_mul_f32_e32 v107, v87, v47
	v_add_f32_dpp v100, v100, v100 quad_perm:[2,3,0,1] row_mask:0xf bank_mask:0xf bound_ctrl:1
	v_fmac_f32_e32 v104, v0, v88
	v_fmac_f32_e32 v105, v1, v89
	v_add_f32_dpp v100, v100, v100 row_half_mirror row_mask:0xf bank_mask:0xf bound_ctrl:1
	v_fmac_f32_e32 v106, v2, v90
	v_fmac_f32_e32 v107, v3, v91
	v_add_f32_dpp v100, v100, v100 row_mirror row_mask:0xf bank_mask:0xf bound_ctrl:1
	v_fma_f32 v0, -v92, v100, v104
	v_fma_f32 v1, -v93, v100, v105
	v_fma_f32 v2, -v94, v100, v106
	v_fma_f32 v3, -v95, v100, v107
	v_mul_f32_e32 v101, v0, v96
	v_fmac_f32_e32 v101, v1, v97
	v_fmac_f32_e32 v101, v2, v98
	v_fmac_f32_e32 v101, v3, v99
	ds_write_b32 v33, v101 offset:7168
	ds_read_b128 v[80:83], v31 offset:11776
	ds_read_b128 v[84:87], v31 offset:12288
	ds_read_b128 v[88:91], v31 offset:11520
	ds_read_b128 v[92:95], v31 offset:12032
	ds_read_b128 v[96:99], v31 offset:12544
	s_waitcnt lgkmcnt(6)
; #define LAS __attribute__((address_space(3)))
; __device__ __forceinline__ float sum16(float x) { x = dpp_add<0xB1>(x); x = dpp_add<0x4E>(x); x = dpp_add<0x141>(x); x = dpp_add<0x140>(x); return x; }
; __device__ __forceinline__ void scan_step(f32x4& S, const ScanOps& o, LAS float* yp) {
;     f32x2 S0 = {S[0], S[1]}, S1 = {S[2], S[3]};
;     const f32x2 k0 = {o.kk[0], o.kk[1]}, k1 = {o.kk[2], o.kk[3]};
;     f32x2 t = S0 * k0; t = S1 * k1 + t;
;     const float sa = -sum16(t[0] + t[1]);
;     const f32x2 sav = {sa, sa}, vv = {o.v, o.v};
;     const f32x2 a0 = {o.ka[0], o.ka[1]}, a1 = {o.ka[2], o.ka[3]}, p0 = {o.kp[0], o.kp[1]}, p1 = {o.kp[2], o.kp[3]}, w0 = {o.w[0], o.w[1]}, w1 = {o.w[2], o.w[3]};
;     f32x2 u0 = a0 * sav; u0 = p0 * vv + u0; S0 = S0 * w0 + u0;
;     f32x2 u1 = a1 * sav; u1 = p1 * vv + u1; S1 = S1 * w1 + u1;
;     const f32x2 r0 = {o.rr[0], o.rr[1]}, r1 = {o.rr[2], o.rr[3]};
;     f32x2 y = S0 * r0; y = S1 * r1 + y;
;     *yp = y[0] + y[1];
;     S = (f32x4){S0[0], S0[1], S1[0], S1[1]};
; }
; __device__ __forceinline__ void scan_unit(const Ctx& p, int chain, int rq, LAS unsigned char* lds) {
;     ...
;             for (int t = 0; t < SCH; t += 2) {
;                 scan_load(ob, OP, VP, t + 1);
;                 oa.v = vv[0]; ob.v = vv[1];
;                 scan_step(S, oa, Y + t * 256);
;                 scan_load(oa, OP, VP, (t + 2) & (SCH - 1));
;                 vv = *(const LAS f32x2*)(VP + ((t + 2) & (SCH - 1)));
;                 scan_step(S, ob, Y + (t + 1) * 256);
;             }
	v_mul_f32_e32 v100, v0, v60
	v_fmac_f32_e32 v100, v1, v61
	v_fmac_f32_e32 v100, v2, v62
	v_fmac_f32_e32 v100, v3, v63
	v_mul_f32_e32 v104, v64, v48
	v_mul_f32_e64 v105, v65, v48
	v_add_f32_dpp v100, v100, v100 quad_perm:[1,0,3,2] row_mask:0xf bank_mask:0xf bound_ctrl:1
	v_mul_f32_e32 v106, v66, v48
	v_mul_f32_e32 v107, v67, v48
	v_add_f32_dpp v100, v100, v100 quad_perm:[2,3,0,1] row_mask:0xf bank_mask:0xf bound_ctrl:1
	v_fmac_f32_e32 v104, v0, v68
	v_fmac_f32_e32 v105, v1, v69
	v_add_f32_dpp v100, v100, v100 row_half_mirror row_mask:0xf bank_mask:0xf bound_ctrl:1
	v_fmac_f32_e32 v106, v2, v70
	v_fmac_f32_e32 v107, v3, v71
	v_add_f32_dpp v100, v100, v100 row_mirror row_mask:0xf bank_mask:0xf bound_ctrl:1
	v_fma_f32 v0, -v72, v100, v104
	v_fma_f32 v1, -v73, v100, v105
	v_fma_f32 v2, -v74, v100, v106
	v_fma_f32 v3, -v75, v100, v107
	v_mul_f32_e32 v101, v0, v76
	v_fmac_f32_e32 v101, v1, v77
	v_fmac_f32_e32 v101, v2, v78
	v_fmac_f32_e32 v101, v3, v79
	ds_write_b32 v33, v101 offset:8192
	ds_read_b128 v[60:63], v31 offset:13056
	ds_read_b128 v[64:67], v31 offset:13568
	ds_read_b128 v[68:71], v31 offset:12800
	ds_read_b128 v[72:75], v31 offset:13312
	ds_read_b128 v[76:79], v31 offset:13824
	s_waitcnt lgkmcnt(6)
	v_mul_f32_e32 v100, v0, v80
	v_fmac_f32_e32 v100, v1, v81
	v_fmac_f32_e32 v100, v2, v82
	v_fmac_f32_e32 v100, v3, v83
	v_mul_f32_e32 v104, v84, v49
	v_mul_f32_e64 v105, v85, v49
	v_add_f32_dpp v100, v100, v100 quad_perm:[1,0,3,2] row_mask:0xf bank_mask:0xf bound_ctrl:1
	v_mul_f32_e32 v106, v86, v49
	v_mul_f32_e32 v107, v87, v49
	v_add_f32_dpp v100, v100, v100 quad_perm:[2,3,0,1] row_mask:0xf bank_mask:0xf bound_ctrl:1
	v_fmac_f32_e32 v104, v0, v88
	v_fmac_f32_e32 v105, v1, v89
	v_add_f32_dpp v100, v100, v100 row_half_mirror row_mask:0xf bank_mask:0xf bound_ctrl:1
	v_fmac_f32_e32 v106, v2, v90
	v_fmac_f32_e32 v107, v3, v91
	v_add_f32_dpp v100, v100, v100 row_mirror row_mask:0xf bank_mask:0xf bound_ctrl:1
	v_fma_f32 v0, -v92, v100, v104
	v_fma_f32 v1, -v93, v100, v105
	v_fma_f32 v2, -v94, v100, v106
	v_fma_f32 v3, -v95, v100, v107
	v_mul_f32_e32 v101, v0, v96
	v_fmac_f32_e32 v101, v1, v97
	v_fmac_f32_e32 v101, v2, v98
	v_fmac_f32_e32 v101, v3, v99
	ds_write_b32 v33, v101 offset:9216
	ds_read_b128 v[80:83], v31 offset:14336
	ds_read_b128 v[84:87], v31 offset:14848
	ds_read_b128 v[88:91], v31 offset:14080
	ds_read_b128 v[92:95], v31 offset:14592
	ds_read_b128 v[96:99], v31 offset:15104
	s_waitcnt lgkmcnt(6)
	v_mul_f32_e32 v100, v0, v60
	v_fmac_f32_e32 v100, v1, v61
	v_fmac_f32_e32 v100, v2, v62
	v_fmac_f32_e32 v100, v3, v63
	v_mul_f32_e32 v104, v64, v50
	v_mul_f32_e64 v105, v65, v50
	v_add_f32_dpp v100, v100, v100 quad_perm:[1,0,3,2] row_mask:0xf bank_mask:0xf bound_ctrl:1
	v_mul_f32_e32 v106, v66, v50
	v_mul_f32_e32 v107, v67, v50
	v_add_f32_dpp v100, v100, v100 quad_perm:[2,3,0,1] row_mask:0xf bank_mask:0xf bound_ctrl:1
	v_fmac_f32_e32 v104, v0, v68
	v_fmac_f32_e32 v105, v1, v69
	v_add_f32_dpp v100, v100, v100 row_half_mirror row_mask:0xf bank_mask:0xf bound_ctrl:1
	v_fmac_f32_e32 v106, v2, v70
	v_fmac_f32_e32 v107, v3, v71
	v_add_f32_dpp v100, v100, v100 row_mirror row_mask:0xf bank_mask:0xf bound_ctrl:1
	v_fma_f32 v0, -v72, v100, v104
	v_fma_f32 v1, -v73, v100, v105
	v_fma_f32 v2, -v74, v100, v106
	v_fma_f32 v3, -v75, v100, v107
	v_mul_f32_e32 v101, v0, v76
	v_fmac_f32_e32 v101, v1, v77
	v_fmac_f32_e32 v101, v2, v78
	v_fmac_f32_e32 v101, v3, v79
	ds_write_b32 v33, v101 offset:10240
	ds_read_b128 v[60:63], v31 offset:15616
	ds_read_b128 v[64:67], v31 offset:16128
	ds_read_b128 v[68:71], v31 offset:15360
	ds_read_b128 v[72:75], v31 offset:15872
	ds_read_b128 v[76:79], v31 offset:16384
	s_waitcnt lgkmcnt(6)
	v_mul_f32_e32 v100, v0, v80
	v_fmac_f32_e32 v100, v1, v81
	v_fmac_f32_e32 v100, v2, v82
	v_fmac_f32_e32 v100, v3, v83
	v_mul_f32_e32 v104, v84, v51
	v_mul_f32_e64 v105, v85, v51
	v_add_f32_dpp v100, v100, v100 quad_perm:[1,0,3,2] row_mask:0xf bank_mask:0xf bound_ctrl:1
	v_mul_f32_e32 v106, v86, v51
	v_mul_f32_e32 v107, v87, v51
	v_add_f32_dpp v100, v100, v100 quad_perm:[2,3,0,1] row_mask:0xf bank_mask:0xf bound_ctrl:1
	v_fmac_f32_e32 v104, v0, v88
	v_fmac_f32_e32 v105, v1, v89
	v_add_f32_dpp v100, v100, v100 row_half_mirror row_mask:0xf bank_mask:0xf bound_ctrl:1
	v_fmac_f32_e32 v106, v2, v90
	v_fmac_f32_e32 v107, v3, v91
	v_add_f32_dpp v100, v100, v100 row_mirror row_mask:0xf bank_mask:0xf bound_ctrl:1
	v_fma_f32 v0, -v92, v100, v104
	v_fma_f32 v1, -v93, v100, v105
	v_fma_f32 v2, -v94, v100, v106
	v_fma_f32 v3, -v95, v100, v107
	v_mul_f32_e32 v101, v0, v96
	v_fmac_f32_e32 v101, v1, v97
	v_fmac_f32_e32 v101, v2, v98
	v_fmac_f32_e32 v101, v3, v99
	ds_write_b32 v33, v101 offset:11264
	ds_read_b128 v[80:83], v31 offset:16896
	ds_read_b128 v[84:87], v31 offset:17408
	ds_read_b128 v[88:91], v31 offset:16640
	ds_read_b128 v[92:95], v31 offset:17152
	ds_read_b128 v[96:99], v31 offset:17664
	s_waitcnt lgkmcnt(6)
; #define LAS __attribute__((address_space(3)))
; __device__ __forceinline__ float sum16(float x) { x = dpp_add<0xB1>(x); x = dpp_add<0x4E>(x); x = dpp_add<0x141>(x); x = dpp_add<0x140>(x); return x; }
; __device__ __forceinline__ void scan_step(f32x4& S, const ScanOps& o, LAS float* yp) {
;     f32x2 S0 = {S[0], S[1]}, S1 = {S[2], S[3]};
;     const f32x2 k0 = {o.kk[0], o.kk[1]}, k1 = {o.kk[2], o.kk[3]};
;     f32x2 t = S0 * k0; t = S1 * k1 + t;
;     const float sa = -sum16(t[0] + t[1]);
;     const f32x2 sav = {sa, sa}, vv = {o.v, o.v};
;     const f32x2 a0 = {o.ka[0], o.ka[1]}, a1 = {o.ka[2], o.ka[3]}, p0 = {o.kp[0], o.kp[1]}, p1 = {o.kp[2], o.kp[3]}, w0 = {o.w[0], o.w[1]}, w1 = {o.w[2], o.w[3]};
;     f32x2 u0 = a0 * sav; u0 = p0 * vv + u0; S0 = S0 * w0 + u0;
;     f32x2 u1 = a1 * sav; u1 = p1 * vv + u1; S1 = S1 * w1 + u1;
;     const f32x2 r0 = {o.rr[0], o.rr[1]}, r1 = {o.rr[2], o.rr[3]};
;     f32x2 y = S0 * r0; y = S1 * r1 + y;
;     *yp = y[0] + y[1];
;     S = (f32x4){S0[0], S0[1], S1[0], S1[1]};
; }
; __device__ __forceinline__ void scan_unit(const Ctx& p, int chain, int rq, LAS unsigned char* lds) {
;     ...
;         for (int ci = 0; ci < nch; ++ci) {
;             __syncthreads();
;             const LAS float* OP = B0 + (ci & 1) * SBUF_F + 4 * cl;
;             const LAS float* VP = B0 + (ci & 1) * SBUF_F + SCH * 320 + il * 16;
;             LAS float* Y = YB + (ci & 1) * YP_F + il * 16 + cl;
;             ScanOps oa, ob;
;             scan_load(oa, OP, VP, 0);
;             f32x2 vv = *(const LAS f32x2*)VP;
; #pragma unroll 1
;             for (int t = 0; t < SCH; t += 2) {
;                 scan_load(ob, OP, VP, t + 1);
;                 oa.v = vv[0]; ob.v = vv[1];
;                 scan_step(S, oa, Y + t * 256);
;                 scan_load(oa, OP, VP, (t + 2) & (SCH - 1));
;                 vv = *(const LAS f32x2*)(VP + ((t + 2) & (SCH - 1)));
;                 scan_step(S, ob, Y + (t + 1) * 256);
;             }
;         }
;         __syncthreads();
;         *(f32x4*)sg = S;
	v_mul_f32_e32 v100, v0, v60
	v_fmac_f32_e32 v100, v1, v61
	v_fmac_f32_e32 v100, v2, v62
	v_fmac_f32_e32 v100, v3, v63
	v_mul_f32_e32 v104, v64, v52
	v_mul_f32_e64 v105, v65, v52
	v_add_f32_dpp v100, v100, v100 quad_perm:[1,0,3,2] row_mask:0xf bank_mask:0xf bound_ctrl:1
	v_mul_f32_e32 v106, v66, v52
	v_mul_f32_e32 v107, v67, v52
	v_add_f32_dpp v100, v100, v100 quad_perm:[2,3,0,1] row_mask:0xf bank_mask:0xf bound_ctrl:1
	v_fmac_f32_e32 v104, v0, v68
	v_fmac_f32_e32 v105, v1, v69
	v_add_f32_dpp v100, v100, v100 row_half_mirror row_mask:0xf bank_mask:0xf bound_ctrl:1
	v_fmac_f32_e32 v106, v2, v70
	v_fmac_f32_e32 v107, v3, v71
	v_add_f32_dpp v100, v100, v100 row_mirror row_mask:0xf bank_mask:0xf bound_ctrl:1
	v_fma_f32 v0, -v72, v100, v104
	v_fma_f32 v1, -v73, v100, v105
	v_fma_f32 v2, -v74, v100, v106
	v_fma_f32 v3, -v75, v100, v107
	v_mul_f32_e32 v101, v0, v76
	v_fmac_f32_e32 v101, v1, v77
	v_fmac_f32_e32 v101, v2, v78
	v_fmac_f32_e32 v101, v3, v79
	ds_write_b32 v33, v101 offset:12288
	ds_read_b128 v[60:63], v31 offset:18176
	ds_read_b128 v[64:67], v31 offset:18688
	ds_read_b128 v[68:71], v31 offset:17920
	ds_read_b128 v[72:75], v31 offset:18432
	ds_read_b128 v[76:79], v31 offset:18944
	s_waitcnt lgkmcnt(6)
	v_mul_f32_e32 v100, v0, v80
	v_fmac_f32_e32 v100, v1, v81
	v_fmac_f32_e32 v100, v2, v82
	v_fmac_f32_e32 v100, v3, v83
	v_mul_f32_e32 v104, v84, v53
	v_mul_f32_e64 v105, v85, v53
	v_add_f32_dpp v100, v100, v100 quad_perm:[1,0,3,2] row_mask:0xf bank_mask:0xf bound_ctrl:1
	v_mul_f32_e32 v106, v86, v53
	v_mul_f32_e32 v107, v87, v53
	v_add_f32_dpp v100, v100, v100 quad_perm:[2,3,0,1] row_mask:0xf bank_mask:0xf bound_ctrl:1
	v_fmac_f32_e32 v104, v0, v88
	v_fmac_f32_e32 v105, v1, v89
	v_add_f32_dpp v100, v100, v100 row_half_mirror row_mask:0xf bank_mask:0xf bound_ctrl:1
	v_fmac_f32_e32 v106, v2, v90
	v_fmac_f32_e32 v107, v3, v91
	v_add_f32_dpp v100, v100, v100 row_mirror row_mask:0xf bank_mask:0xf bound_ctrl:1
	v_fma_f32 v0, -v92, v100, v104
	v_fma_f32 v1, -v93, v100, v105
	v_fma_f32 v2, -v94, v100, v106
	v_fma_f32 v3, -v95, v100, v107
	v_mul_f32_e32 v101, v0, v96
	v_fmac_f32_e32 v101, v1, v97
	v_fmac_f32_e32 v101, v2, v98
	v_fmac_f32_e32 v101, v3, v99
	ds_write_b32 v33, v101 offset:13312
	ds_read_b128 v[80:83], v31 offset:19456
	ds_read_b128 v[84:87], v31 offset:19968
	ds_read_b128 v[88:91], v31 offset:19200
	ds_read_b128 v[92:95], v31 offset:19712
	ds_read_b128 v[96:99], v31 offset:20224
	s_waitcnt lgkmcnt(6)
	v_mul_f32_e32 v100, v0, v60
	v_fmac_f32_e32 v100, v1, v61
	v_fmac_f32_e32 v100, v2, v62
	v_fmac_f32_e32 v100, v3, v63
	v_mul_f32_e32 v104, v64, v54
	v_mul_f32_e64 v105, v65, v54
	v_add_f32_dpp v100, v100, v100 quad_perm:[1,0,3,2] row_mask:0xf bank_mask:0xf bound_ctrl:1
	v_mul_f32_e32 v106, v66, v54
	v_mul_f32_e32 v107, v67, v54
	v_add_f32_dpp v100, v100, v100 quad_perm:[2,3,0,1] row_mask:0xf bank_mask:0xf bound_ctrl:1
	v_fmac_f32_e32 v104, v0, v68
	v_fmac_f32_e32 v105, v1, v69
	v_add_f32_dpp v100, v100, v100 row_half_mirror row_mask:0xf bank_mask:0xf bound_ctrl:1
	v_fmac_f32_e32 v106, v2, v70
	v_fmac_f32_e32 v107, v3, v71
	v_add_f32_dpp v100, v100, v100 row_mirror row_mask:0xf bank_mask:0xf bound_ctrl:1
	v_fma_f32 v0, -v72, v100, v104
	v_fma_f32 v1, -v73, v100, v105
	v_fma_f32 v2, -v74, v100, v106
	v_fma_f32 v3, -v75, v100, v107
	v_mul_f32_e32 v101, v0, v76
	v_fmac_f32_e32 v101, v1, v77
	v_fmac_f32_e32 v101, v2, v78
	v_fmac_f32_e32 v101, v3, v79
	ds_write_b32 v33, v101 offset:14336
	s_waitcnt lgkmcnt(1)
	v_mul_f32_e32 v100, v0, v80
	v_fmac_f32_e32 v100, v1, v81
	v_fmac_f32_e32 v100, v2, v82
	v_fmac_f32_e32 v100, v3, v83
	v_mul_f32_e32 v104, v84, v55
	v_mul_f32_e64 v105, v85, v55
	v_add_f32_dpp v100, v100, v100 quad_perm:[1,0,3,2] row_mask:0xf bank_mask:0xf bound_ctrl:1
	v_mul_f32_e32 v106, v86, v55
	v_mul_f32_e32 v107, v87, v55
	v_add_f32_dpp v100, v100, v100 quad_perm:[2,3,0,1] row_mask:0xf bank_mask:0xf bound_ctrl:1
	v_fmac_f32_e32 v104, v0, v88
	v_fmac_f32_e32 v105, v1, v89
	v_add_f32_dpp v100, v100, v100 row_half_mirror row_mask:0xf bank_mask:0xf bound_ctrl:1
	v_fmac_f32_e32 v106, v2, v90
	v_fmac_f32_e32 v107, v3, v91
	v_add_f32_dpp v100, v100, v100 row_mirror row_mask:0xf bank_mask:0xf bound_ctrl:1
	v_fma_f32 v0, -v92, v100, v104
	v_fma_f32 v1, -v93, v100, v105
	v_fma_f32 v2, -v94, v100, v106
	v_fma_f32 v3, -v95, v100, v107
	v_mul_f32_e32 v101, v0, v96
	v_fmac_f32_e32 v101, v1, v97
	v_fmac_f32_e32 v101, v2, v98
	v_fmac_f32_e32 v101, v3, v99
	ds_write_b32 v33, v101 offset:15360
	s_add_i32 s10, s10, 1
	s_cmpk_eq_i32 s10, 0x100
	s_cbranch_scc0 .LBB0_1714
	s_setprio 0
	s_lshl_b32 s8, s28, 12
	v_lshl_or_b32 v4, v27, 8, s8
	v_mov_b32_e32 v5, 0
	v_lshl_add_u64 v[6:7], s[2:3], 0, v[4:5]
	v_lshlrev_b32_e32 v4, 2, v26
	v_lshl_add_u64 v[4:5], v[6:7], 0, v[4:5]
	v_add_co_u32_e32 v4, vcc, 0x8080000, v4
	s_mov_b64 s[2:3], 0
	s_nop 0
	v_addc_co_u32_e32 v5, vcc, 0, v5, vcc
	s_waitcnt lgkmcnt(0)
	s_barrier
	global_store_dwordx4 v[4:5], v[0:3], off
